# tilewait
# speedup vs baseline: 1.0263x; 1.0096x over previous
; #define WAIT_V(n) asm volatile("s_waitcnt vmcnt(" #n ")" ::: "memory")
; #define BAR __builtin_amdgcn_s_barrier()
; template <int EPI>
; __device__ __forceinline__ void gemm_phase(const u16* __restrict__ A, const u16* __restrict__ Bt, const int K,
;                                            const int nN, char* shm, const EpiArgs& ea) {
;     ...
;     WAIT_V(0);
;     if (wr == 1) BAR;
;     BAR;
;     BAR;
.LBB0_169:
	s_waitcnt vmcnt(8)
	s_andn2_b64 vcc, exec, s[24:25]
	s_cbranch_vccnz .LBB0_171
	s_barrier

; #define WAIT_V(n) asm volatile("s_waitcnt vmcnt(" #n ")" ::: "memory")
; template <int EPI>
; __device__ __forceinline__ void gemm_phase(const u16* __restrict__ A, const u16* __restrict__ Bt, const int K,
;                                            const int nN, char* shm, const EpiArgs& ea) {
;   const int tid = threadIdx.x;
;   const int wid = __builtin_amdgcn_readfirstlane(tid >> 6);
;   const int lane = tid & 63;
;   const int wr = wid >> 2, wc = wid & 3, fr = lane & 15, fq = lane >> 4;
;   __amdgpu_buffer_rsrc_t rA = __builtin_amdgcn_make_buffer_rsrc((void*)A, (short)0, 0x7FFFFFFF, 0x00020000);
;   __amdgpu_buffer_rsrc_t rB = __builtin_amdgcn_make_buffer_rsrc((void*)Bt, (short)0, 0x7FFFFFFF, 0x00020000);
;   const int voff0 = tid * 16;
;   const int ldsw = wid * 1024;
;   const int KT = K >> 6;
;     ...
;     WAIT_V(0);
.LBB0_223:
	s_andn2_b64 vcc, exec, s[4:5]
	s_cbranch_vccnz .LBB0_252
	s_add_u32 s18, s90, 0xe620000
	s_addc_u32 s19, s91, 0
	s_add_u32 s28, s90, 0x1da20000
	s_addc_u32 s29, s91, 0
	s_lshr_b32 s26, s6, 8
	s_and_b32 s27, s30, 3
	s_waitcnt vmcnt(2)
	v_lshlrev_b32_e32 v3, 6, v174
	s_waitcnt vmcnt(1)
	v_lshlrev_b32_e32 v4, 2, v174
	s_cmp_eq_u32 s26, 1
	v_and_b32_e32 v2, 48, v174
	v_and_b32_e32 v3, 0x3c0, v3
	v_and_b32_e32 v4, 32, v4
	s_cselect_b64 s[4:5], -1, 0
	v_bitop3_b32 v3, v3, v4, v2 bitop3:0x36
	s_add_i32 s52, 16, 0x10000
	s_add_i32 s55, 16, 0x14000
	s_add_i32 s59, 16, 0x18000
	s_add_i32 s63, 16, 0x1c000
	v_add_u32_e32 v5, s52, v3
	s_add_i32 s43, s7, 16
	v_add_u32_e32 v6, s55, v3
	s_add_i32 s52, s52, s7
	s_add_i32 s55, s55, s7
	v_add_u32_e32 v7, s59, v3
	v_add_u32_e32 v8, s63, v3
	s_add_i32 s59, s59, s7
	s_add_i32 s63, s63, s7
	s_lshl_b32 s34, s27, 12
	s_add_i32 s48, s43, 0xc000
	s_add_i32 s49, s43, 0xe000
	s_add_i32 s53, s52, 0x2000
	s_add_i32 s54, s43, 0x2000
	s_add_i32 s56, s55, 0x2000
	s_add_i32 s57, s43, 0x4000
	s_add_i32 s58, s43, 0x6000
	s_add_i32 s60, s59, 0x2000
	s_add_i32 s61, s43, 0x8000
	s_add_i32 s62, s43, 0xa000
	s_add_i32 s64, s63, 0x2000
	v_and_b32_e32 v0, 15, v174
	s_cmpk_lt_u32 s6, 0x100
	v_bfe_u32 v1, v174, 4, 2
	s_cselect_b64 s[30:31], -1, 0
	v_lshl_or_b32 v135, s26, 6, v0
	s_lshl_b32 s26, s26, 13
	v_lshl_or_b32 v0, v0, 6, v2
	v_lshrrev_b32_e32 v9, 2, v174
	s_lshl_b32 s65, s27, 5
	v_lshlrev_b32_e32 v136, 2, v1
	v_and_b32_e32 v10, 16, v174
	v_cmp_eq_u32_e64 s[6:7], 0, v1
	v_xad_u32 v0, v0, v4, 16
	v_add_u32_e32 v1, 16, v3
	s_or_b32 s27, s26, 0x800
	s_or_b32 s38, s26, 0x1000
	s_or_b32 s39, s26, 0x1800
	v_cndmask_b32_e64 v2, 0, 1, s[4:5]
	s_movk_i32 s42, 0x3c0
	v_and_or_b32 v137, v9, 8, v10
	s_mov_b32 s66, 0
	v_cmp_ne_u32_e64 s[4:5], 1, v2
	v_add_u32_e32 v138, s34, v5
	v_add_u32_e32 v139, s26, v0
	v_add_u32_e32 v140, s27, v1
	v_add_u32_e32 v141, s38, v1
	v_add_u32_e32 v142, s39, v1
	v_add_u32_e32 v143, s34, v6
	v_add_u32_e32 v144, s34, v7
	v_add_u32_e32 v145, s34, v8
	v_mov_b32_e32 v129, 0
	s_mov_b32 s34, 0x3f9837f0
	s_waitcnt vmcnt(0)
	s_branch .LBB0_226

; #define WAIT_V(n) asm volatile("s_waitcnt vmcnt(" #n ")" ::: "memory")
; #define BAR __builtin_amdgcn_s_barrier()
; template <int EPI>
; __device__ __forceinline__ void gemm_phase(const u16* __restrict__ A, const u16* __restrict__ Bt, const int K,
;                                            const int nN, char* shm, const EpiArgs& ea) {
;     ...
;     WAIT_V(0);
;     if (wr == 1) BAR;
;     BAR;
;     BAR;
.LBB0_228:
	s_waitcnt vmcnt(40)
	s_and_b64 vcc, exec, s[4:5]
	s_cbranch_vccnz .LBB0_230
	s_barrier

; #define WAIT_V(n) asm volatile("s_waitcnt vmcnt(" #n ")" ::: "memory")
; template <int EPI>
; __device__ __forceinline__ void gemm_phase(const u16* __restrict__ A, const u16* __restrict__ Bt, const int K,
;                                            const int nN, char* shm, const EpiArgs& ea) {
;   const int tid = threadIdx.x;
;   const int wid = __builtin_amdgcn_readfirstlane(tid >> 6);
;   const int lane = tid & 63;
;   const int wr = wid >> 2, wc = wid & 3, fr = lane & 15, fq = lane >> 4;
;   __amdgpu_buffer_rsrc_t rA = __builtin_amdgcn_make_buffer_rsrc((void*)A, (short)0, 0x7FFFFFFF, 0x00020000);
;   __amdgpu_buffer_rsrc_t rB = __builtin_amdgcn_make_buffer_rsrc((void*)Bt, (short)0, 0x7FFFFFFF, 0x00020000);
;   const int voff0 = tid * 16;
;   const int ldsw = wid * 1024;
;   const int KT = K >> 6;
;     ...
;     WAIT_V(0);
.LBB0_298:
	s_andn2_b64 vcc, exec, s[4:5]
	s_cbranch_vccnz .LBB0_383
	s_add_u32 s6, s90, 0x1da60000
	s_addc_u32 s7, s91, 0
	s_add_u32 s18, s90, 0x1da65000
	s_addc_u32 s19, s91, 0
	s_add_u32 s28, s90, 0x1da20000
	s_addc_u32 s29, s91, 0
	s_add_u32 s30, s90, 0x12820000
	s_addc_u32 s31, s91, 0
	s_lshr_b32 s4, s38, 8
	s_and_b32 s5, s34, 3
	s_waitcnt vmcnt(2)
	v_lshlrev_b32_e32 v2, 6, v174
	v_lshlrev_b32_e32 v162, 2, v174
	s_cmp_eq_u32 s4, 1
	v_and_b32_e32 v1, 48, v174
	v_and_b32_e32 v2, 0x3c0, v2
	v_and_b32_e32 v3, 32, v162
	s_cselect_b64 s[34:35], -1, 0
	v_bitop3_b32 v2, v2, v3, v1 bitop3:0x36
	s_add_i32 s54, 16, 0x10000
	s_add_i32 s57, 16, 0x14000
	s_add_i32 s61, 16, 0x18000
	s_add_i32 s65, 16, 0x1c000
	s_waitcnt vmcnt(1)
	v_add_u32_e32 v4, s54, v2
	s_add_i32 s49, s36, 16
	v_add_u32_e32 v5, s57, v2
	s_add_i32 s54, s54, s36
	s_add_i32 s57, s57, s36
	v_add_u32_e32 v6, s61, v2
	v_add_u32_e32 v7, s65, v2
	s_add_i32 s61, s61, s36
	s_add_i32 s65, s65, s36
	s_lshl_b32 s26, s5, 12
	s_add_i32 s52, s49, 0xc000
	s_add_i32 s53, s49, 0xe000
	s_add_i32 s55, s54, 0x2000
	s_add_i32 s56, s49, 0x2000
	s_add_i32 s58, s57, 0x2000
	s_add_i32 s59, s49, 0x4000
	s_add_i32 s60, s49, 0x6000
	s_add_i32 s62, s61, 0x2000
	s_add_i32 s63, s49, 0x8000
	s_add_i32 s64, s49, 0xa000
	s_add_i32 s66, s65, 0x2000
	s_cmpk_lt_u32 s38, 0x100
	v_and_b32_e32 v0, 15, v174
	s_cselect_b64 s[36:37], -1, 0
	s_cmpk_gt_u32 s38, 0xff
	s_cselect_b64 s[38:39], -1, 0
	v_lshrrev_b32_e32 v8, 2, v174
	v_lshl_or_b32 v165, s4, 6, v0
	s_lshl_b32 s5, s5, 5
	s_lshl_b32 s4, s4, 13
	v_lshl_or_b32 v0, v0, 6, v1
	v_and_b32_e32 v9, 8, v8
	v_and_b32_e32 v10, 16, v174
	v_xad_u32 v0, v0, v3, 16
	v_add_u32_e32 v1, 16, v2
	s_or_b32 s27, s4, 0x800
	s_or_b32 s40, s4, 0x1000
	s_or_b32 s41, s4, 0x1800
	v_lshlrev_b32_e32 v2, 3, v165
	v_and_or_b32 v3, v8, 12, s5
	v_add_u32_e32 v163, 0xffffff00, v174
	v_add_u32_e32 v164, 16, v162
	v_or3_b32 v166, v10, v9, s5
	v_lshl_add_u32 v167, v3, 2, 16
	v_ashrrev_i32_e32 v175, 31, v174
	s_mov_b32 s67, 0
	v_add_u32_e32 v168, s26, v4
	v_add_u32_e32 v169, s4, v0
	v_add_u32_e32 v170, s27, v1
	v_add_u32_e32 v171, s40, v1
	v_add_u32_e32 v172, s41, v1
	v_add_u32_e32 v173, s26, v5
	v_add_u32_e32 v176, s26, v6
	v_add_u32_e32 v177, s26, v7
	s_mov_b32 s68, 0x800000
	s_movk_i32 s69, 0x2800
	v_add_u32_e32 v178, 16, v2
	s_waitcnt vmcnt(0)
	s_branch .LBB0_301

; #define WAIT_V(n) asm volatile("s_waitcnt vmcnt(" #n ")" ::: "memory")
; #define BAR __builtin_amdgcn_s_barrier()
; template <int EPI>
; __device__ __forceinline__ void gemm_phase(const u16* __restrict__ A, const u16* __restrict__ Bt, const int K,
;                                            const int nN, char* shm, const EpiArgs& ea) {
;     ...
;     WAIT_V(0);
;     if (wr == 1) BAR;
;     BAR;
;     BAR;
.LBB0_303:
	s_waitcnt vmcnt(16)
	s_andn2_b64 vcc, exec, s[34:35]
	s_cbranch_vccnz .LBB0_305
	s_barrier

; #define WAIT_V(n) asm volatile("s_waitcnt vmcnt(" #n ")" ::: "memory")
; template <int EPI>
; __device__ __forceinline__ void gemm_phase(const u16* __restrict__ A, const u16* __restrict__ Bt, const int K,
;                                            const int nN, char* shm, const EpiArgs& ea) {
;   const int tid = threadIdx.x;
;   const int wid = __builtin_amdgcn_readfirstlane(tid >> 6);
;   const int lane = tid & 63;
;   const int wr = wid >> 2, wc = wid & 3, fr = lane & 15, fq = lane >> 4;
;   __amdgpu_buffer_rsrc_t rA = __builtin_amdgcn_make_buffer_rsrc((void*)A, (short)0, 0x7FFFFFFF, 0x00020000);
;   __amdgpu_buffer_rsrc_t rB = __builtin_amdgcn_make_buffer_rsrc((void*)Bt, (short)0, 0x7FFFFFFF, 0x00020000);
;   const int voff0 = tid * 16;
;   const int ldsw = wid * 1024;
;   const int KT = K >> 6;
;     ...
;     WAIT_V(0);
.LBB0_484:
	s_andn2_b64 vcc, exec, s[4:5]
	s_cbranch_vccnz .LBB0_513
	s_add_u32 s6, s90, 0x1da20000
	s_addc_u32 s7, s91, 0
	s_add_u32 s12, s90, 0x1da40000
	s_addc_u32 s13, s91, 0
	s_add_u32 s14, s90, 0xe620000
	s_addc_u32 s15, s91, 0
	s_lshr_b32 s10, s18, 8
	s_and_b32 s4, s16, 3
	s_waitcnt vmcnt(2)
	v_lshlrev_b32_e32 v3, 6, v174
	s_waitcnt vmcnt(1)
	v_lshlrev_b32_e32 v4, 2, v174
	s_cmp_eq_u32 s10, 1
	v_and_b32_e32 v2, 48, v174
	v_and_b32_e32 v3, 0x3c0, v3
	v_and_b32_e32 v4, 32, v4
	s_cselect_b64 s[16:17], -1, 0
	v_bitop3_b32 v3, v3, v4, v2 bitop3:0x36
	s_add_i32 s36, 16, 0x10000
	s_add_i32 s39, 16, 0x14000
	s_add_i32 s43, 16, 0x18000
	s_add_i32 s51, 16, 0x1c000
	v_add_u32_e32 v5, s36, v3
	s_add_i32 s27, s19, 16
	v_add_u32_e32 v6, s39, v3
	s_add_i32 s36, s36, s19
	s_add_i32 s39, s39, s19
	v_add_u32_e32 v7, s43, v3
	v_add_u32_e32 v8, s51, v3
	s_add_i32 s43, s43, s19
	s_add_i32 s51, s51, s19
	s_lshl_b32 s11, s4, 12
	s_add_i32 s34, s27, 0xc000
	s_add_i32 s35, s27, 0xe000
	s_add_i32 s37, s36, 0x2000
	s_add_i32 s38, s27, 0x2000
	s_add_i32 s40, s39, 0x2000
	s_add_i32 s41, s27, 0x4000
	s_add_i32 s42, s27, 0x6000
	s_add_i32 s48, s43, 0x2000
	s_add_i32 s49, s27, 0x8000
	s_add_i32 s50, s27, 0xa000
	s_add_i32 s52, s51, 0x2000
	v_and_b32_e32 v0, 15, v174
	s_cmpk_lt_u32 s18, 0x100
	v_bfe_u32 v1, v174, 4, 2
	s_cselect_b64 s[18:19], -1, 0
	v_lshl_or_b32 v143, s10, 6, v0
	s_lshl_b32 s10, s10, 13
	v_lshl_or_b32 v0, v0, 6, v2
	v_lshrrev_b32_e32 v9, 2, v174
	s_lshl_b32 s53, s4, 5
	v_lshlrev_b32_e32 v144, 2, v1
	v_and_b32_e32 v10, 16, v174
	v_cmp_eq_u32_e64 s[4:5], 0, v1
	v_xad_u32 v0, v0, v4, 16
	v_add_u32_e32 v1, 16, v3
	s_or_b32 s24, s10, 0x800
	s_or_b32 s26, s10, 0x1000
	s_or_b32 s28, s10, 0x1800
	v_and_or_b32 v145, v9, 8, v10
	s_mov_b32 s54, 0
	v_add_u32_e32 v146, s11, v5
	v_add_u32_e32 v147, s10, v0
	v_add_u32_e32 v148, s24, v1
	v_add_u32_e32 v149, s26, v1
	v_add_u32_e32 v150, s28, v1
	v_add_u32_e32 v151, s11, v6
	v_add_u32_e32 v152, s11, v7
	v_add_u32_e32 v153, s11, v8
	s_mov_b32 s24, 0x3a000000
	s_mov_b32 s55, 0x800000
	v_mov_b32_e32 v129, 0
	s_mov_b32 s26, 0x3f9837f0
	s_waitcnt vmcnt(0)
	s_branch .LBB0_487

; #define WAIT_V(n) asm volatile("s_waitcnt vmcnt(" #n ")" ::: "memory")
; #define BAR __builtin_amdgcn_s_barrier()
; template <int EPI>
; __device__ __forceinline__ void gemm_phase(const u16* __restrict__ A, const u16* __restrict__ Bt, const int K,
;                                            const int nN, char* shm, const EpiArgs& ea) {
;     ...
;     WAIT_V(0);
;     if (wr == 1) BAR;
;     BAR;
;     BAR;
.LBB0_489:
	s_waitcnt vmcnt(40)
	s_andn2_b64 vcc, exec, s[16:17]
	s_cbranch_vccnz .LBB0_491
	s_barrier

; template <int EPI>
; __device__ __forceinline__ void gemm_phase(const u16* __restrict__ A, const u16* __restrict__ Bt, const int K,
;                                            const int nN, char* shm, const EpiArgs& ea) {
;     ...
;   const int nM = M_TOK / BM;
;   const int nwg = nM * nN;
;   const int G = gridDim.x, bid = blockIdx.x;
;   const bool remap = ((G & 7) == 0) && (nwg % G == 0);
;   const int nig = 8 * nN;
;   const int nt = K / BK;
;   const int Lofs = remap ? (bid & 7) * (G >> 3) + (bid >> 3) : bid;
;   int brow = 0, bcol = 0, pn = 0;
;   if (Lofs < nwg) {
;     TILE_RC(Lofs, brow, bcol, pn);
;     STAGE7(brow, bcol);
;   }
.LBB0_557:
	s_cmpk_gt_i32 s25, 0xaff
	s_cbranch_scc1 .LBB0_578
	s_add_u32 s8, s90, 0x1da6a000
	s_addc_u32 s9, s91, 0
	s_add_u32 s10, s90, 0x1da40000
	s_addc_u32 s11, s91, 0
	s_add_u32 s12, s90, 0x12820000
	s_addc_u32 s13, s91, 0
	s_add_u32 s0, s90, 0xe620000
	s_addc_u32 s1, s91, 0
	s_add_u32 s4, s90, 0x6080000
	s_mul_hi_i32 s15, s25, 0x2e8ba2e9
	s_addc_u32 s5, s91, 0
	s_lshr_b32 s16, s15, 31
	s_ashr_i32 s15, s15, 6
	s_add_i32 s15, s15, s16
	s_lshl_b32 s16, s15, 3
	s_mulk_i32 s15, 0x160
	s_sub_i32 s15, s25, s15
	s_bfe_u32 s17, s15, 0x3001c
	s_add_i32 s17, s15, s17
	s_lshr_b32 s14, s20, 6
	s_sext_i32_i16 s18, s17
	s_and_b32 s17, s17, 0xfff8
	s_lshl_b32 s14, s14, 10
	s_sub_i32 s15, s15, s17
	s_add_i32 s17, 16, 0x10000
	s_mov_b32 s3, 0x20000
	s_brev_b32 s2, -2
	s_sext_i32_i16 s15, s15
	s_ashr_i32 s55, s18, 3
	s_add_i32 s30, s17, s14
	s_and_b32 s5, s5, 0xffff
	s_mov_b32 s6, s2
	s_mov_b32 s7, s3
	v_lshlrev_b32_e32 v175, 4, v174
	s_add_i32 s15, s16, s15
	s_mul_i32 s16, s55, 0x108000
	s_mov_b32 m0, s30
	s_add_i32 s31, s30, 0x2000
	buffer_load_dwordx4 v175, s[4:7], s16 offen lds
	s_or_b32 s18, s16, 0x2000
	s_mov_b32 m0, s31
	s_add_i32 s33, s14, 16
	s_and_b32 s1, s1, 0xffff
	buffer_load_dwordx4 v175, s[4:7], s18 offen lds
	s_mul_i32 s18, s15, 0x108000
	s_mov_b32 m0, s33
	s_add_i32 s34, s33, 0x2000
	s_add_i32 s21, 16, 0x14000
	buffer_load_dwordx4 v175, s[0:3], s18 offen lds
	s_or_b32 s19, s18, 0x2000
	s_mov_b32 m0, s34
	s_add_i32 s35, s21, s14
	buffer_load_dwordx4 v175, s[0:3], s19 offen lds
	s_add_i32 s19, s16, 0x84000
	s_mov_b32 m0, s35
	s_add_i32 s36, s35, 0x2000
	buffer_load_dwordx4 v175, s[4:7], s19 offen lds
	s_add_i32 s19, s16, 0x86000
	s_mov_b32 m0, s36
	s_add_i32 s37, s33, 0x4000
	buffer_load_dwordx4 v175, s[4:7], s19 offen lds
	s_add_i32 s19, s18, 0x84000
	s_mov_b32 m0, s37
	s_add_i32 s38, s33, 0x6000
	s_add_i32 s24, 16, 0x18000
	buffer_load_dwordx4 v175, s[0:3], s19 offen lds
	s_add_i32 s19, s18, 0x86000
	s_mov_b32 m0, s38
	s_add_i32 s39, s24, s14
	buffer_load_dwordx4 v175, s[0:3], s19 offen lds
	s_or_b32 s19, s16, 0x4000
	s_mov_b32 m0, s39
	s_add_i32 s40, s39, 0x2000
	buffer_load_dwordx4 v175, s[4:7], s19 offen lds
	s_or_b32 s19, s16, 0x6000
	s_mov_b32 m0, s40
	s_add_i32 s41, s33, 0x8000
	buffer_load_dwordx4 v175, s[4:7], s19 offen lds
	s_or_b32 s19, s18, 0x4000
	s_mov_b32 m0, s41
	s_add_i32 s42, s33, 0xa000
	buffer_load_dwordx4 v175, s[0:3], s19 offen lds
	s_add_i32 s19, 16, 0x1c000
	s_or_b32 s18, s18, 0x6000
	s_mov_b32 m0, s42
	s_add_i32 s43, s19, s14
	buffer_load_dwordx4 v175, s[0:3], s18 offen lds
	s_add_i32 s18, s16, 0x88000
	s_mov_b32 m0, s43
	s_add_i32 s44, s43, 0x2000
	buffer_load_dwordx4 v175, s[4:7], s18 offen lds
	s_add_i32 s16, s16, 0x8a000
	s_mov_b32 m0, s44
	s_lshl_b32 s56, s15, 8
	buffer_load_dwordx4 v175, s[4:7], s16 offen lds
	s_lshr_b32 s6, s20, 8
	s_bfe_u32 s7, s20, 0x20006
	s_lshl_b32 s57, s55, 8
	s_cmp_eq_u32 s6, 1
	s_waitcnt vmcnt(16)
	v_lshlrev_b32_e32 v2, 6, v174
	v_lshlrev_b32_e32 v178, 2, v174
	s_cselect_b64 s[14:15], -1, 0
	s_lshl_b32 s26, s7, 12
	v_and_b32_e32 v1, 48, v174
	v_and_b32_e32 v2, 0x3c0, v2
	v_and_b32_e32 v3, 32, v178
	s_lshl_b32 s27, s6, 6
	s_add_i32 s46, s33, 0xc000
	s_add_i32 s47, s33, 0xe000
	v_bitop3_b32 v2, v2, v3, v1 bitop3:0x36
	s_cmpk_lt_u32 s20, 0x100
	v_and_b32_e32 v0, 15, v174
	s_waitcnt vmcnt(15)
	v_add_u32_e32 v4, s17, v2
	s_cselect_b64 s[16:17], -1, 0
	s_cmpk_gt_u32 s20, 0xff
	v_lshrrev_b32_e32 v8, 1, v174
	v_add_u32_e32 v5, s21, v2
	v_add_u32_e32 v7, s19, v2
	s_cselect_b64 s[18:19], -1, 0
	v_and_b32_e32 v8, 16, v8
	v_or_b32_e32 v9, s27, v0
	s_lshr_b32 s21, s20, 1
	s_lshl_b32 s6, s6, 13
	v_lshl_or_b32 v0, v0, 6, v1
	v_add_u32_e32 v6, s24, v2
	s_bfe_u32 s48, s20, 0x10007
	v_and_or_b32 v181, s21, 32, v8
	v_xad_u32 v0, v0, v3, 16
	v_add_u32_e32 v2, 16, v2
	s_or_b32 s20, s6, 0x800
	s_or_b32 s21, s6, 0x1000
	s_or_b32 s24, s6, 0x1800
	v_lshlrev_b32_e32 v3, 3, v9
	v_lshl_or_b32 v1, s7, 7, v1
	s_movk_i32 s45, 0x3c0
	v_add_u32_e32 v179, 16, v178
	v_and_or_b32 v180, v174, 31, s27
	v_add_u32_e32 v182, 16, v1
	s_mov_b32 s49, 0
	v_add_u32_e32 v183, s26, v4
	v_add_u32_e32 v184, s6, v0
	v_add_u32_e32 v185, s20, v2
	v_add_u32_e32 v186, s21, v2
	v_add_u32_e32 v187, s24, v2
	v_add_u32_e32 v188, s26, v5
	v_add_u32_e32 v189, s26, v6
	v_add_u32_e32 v190, s26, v7
	s_mov_b64 s[20:21], 0x1da74c00
	s_mov_b32 s24, 0x3a000000
	s_mov_b32 s50, 0x800000
	v_add_u32_e32 v191, 16, v3
	s_movk_i32 s51, 0x59
	v_mov_b32_e32 v177, 0
	s_waitcnt vmcnt(0)
	s_branch .LBB0_560

; #define WAIT_V(n) asm volatile("s_waitcnt vmcnt(" #n ")" ::: "memory")
; #define BAR __builtin_amdgcn_s_barrier()
; template <int EPI>
; __device__ __forceinline__ void gemm_phase(const u16* __restrict__ A, const u16* __restrict__ Bt, const int K,
;                                            const int nN, char* shm, const EpiArgs& ea) {
;     ...
;     WAIT_V(0);
;     if (wr == 1) BAR;
;     BAR;
;     BAR;
.LBB0_562:
	s_waitcnt vmcnt(8)
	s_andn2_b64 vcc, exec, s[14:15]
	s_cbranch_vccnz .LBB0_564
	s_barrier

; template <int EPI>
; __device__ __forceinline__ void gemm_phase(const u16* __restrict__ A, const u16* __restrict__ Bt, const int K,
;                                            const int nN, char* shm, const EpiArgs& ea) {
;     ...
;   const int nM = M_TOK / BM;
;   const int nwg = nM * nN;
;   const int G = gridDim.x, bid = blockIdx.x;
;   const bool remap = ((G & 7) == 0) && (nwg % G == 0);
;   const int nig = 8 * nN;
;   const int nt = K / BK;
;   const int Lofs = remap ? (bid & 7) * (G >> 3) + (bid >> 3) : bid;
;   int brow = 0, bcol = 0, pn = 0;
;   if (Lofs < nwg) {
;     TILE_RC(Lofs, brow, bcol, pn);
;     STAGE7(brow, bcol);
;   }
.LBB0_623:
	s_cmpk_gt_i32 s17, 0x1ff
	s_cbranch_scc1 .LBB0_636
	s_add_u32 s8, s90, 0x1da40000
	s_addc_u32 s9, s91, 0
	s_add_u32 s10, s90, 0xe620000
	s_addc_u32 s11, s91, 0
	s_add_u32 s0, s90, 0x12820000
	s_addc_u32 s1, s91, 0
	s_add_u32 s4, s90, 0x8de0000
	s_addc_u32 s5, s91, 0
	s_ashr_i32 s13, s17, 31
	s_lshr_b32 s13, s13, 26
	s_add_i32 s13, s17, s13
	s_ashr_i32 s15, s13, 6
	s_and_b32 s13, s13, 0xffc0
	s_sub_i32 s13, s17, s13
	s_bfe_i32 s16, s13, 0x80000
	s_bfe_u32 s16, s16, 0x3000c
	s_add_i32 s16, s13, s16
	s_bfe_i32 s18, s16, 0x80000
	s_and_b32 s16, s16, 0xf8
	s_sub_i32 s13, s13, s16
	s_lshr_b32 s12, s14, 6
	s_lshl_b32 s15, s15, 3
	s_sext_i32_i16 s18, s18
	s_sext_i32_i8 s13, s13
	s_lshl_b32 s12, s12, 10
	s_add_i32 s13, s15, s13
	s_ashr_i32 s15, s18, 3
	s_add_i32 s18, 16, 0x10000
	s_mov_b32 s3, 0x20000
	s_brev_b32 s2, -2
	s_add_i32 s19, s18, s12
	s_and_b32 s5, s5, 0xffff
	s_mov_b32 s6, s2
	s_mov_b32 s7, s3
	v_lshlrev_b32_e32 v138, 4, v174
	s_mul_i32 s16, s15, 0x2c8000
	s_mov_b32 m0, s19
	s_add_i32 s26, s19, 0x2000
	buffer_load_dwordx4 v138, s[4:7], s16 offen lds
	s_or_b32 s20, s16, 0x2000
	s_mov_b32 m0, s26
	s_add_i32 s27, s12, 16
	s_and_b32 s1, s1, 0xffff
	buffer_load_dwordx4 v138, s[4:7], s20 offen lds
	s_mul_i32 s20, s13, 0x2c8000
	s_mov_b32 m0, s27
	s_add_i32 s28, s27, 0x2000
	s_add_i32 s24, 16, 0x14000
	buffer_load_dwordx4 v138, s[0:3], s20 offen lds
	s_or_b32 s21, s20, 0x2000
	s_mov_b32 m0, s28
	s_add_i32 s29, s24, s12
	buffer_load_dwordx4 v138, s[0:3], s21 offen lds
	s_add_i32 s21, s16, 0x164000
	s_mov_b32 m0, s29
	s_add_i32 s30, s29, 0x2000
	buffer_load_dwordx4 v138, s[4:7], s21 offen lds
	s_add_i32 s21, s16, 0x166000
	s_mov_b32 m0, s30
	s_add_i32 s31, s27, 0x4000
	buffer_load_dwordx4 v138, s[4:7], s21 offen lds
	s_add_i32 s21, s20, 0x164000
	s_mov_b32 m0, s31
	s_add_i32 s34, s27, 0x6000
	s_add_i32 s25, 16, 0x18000
	buffer_load_dwordx4 v138, s[0:3], s21 offen lds
	s_add_i32 s21, s20, 0x166000
	s_mov_b32 m0, s34
	s_add_i32 s35, s25, s12
	buffer_load_dwordx4 v138, s[0:3], s21 offen lds
	s_or_b32 s21, s16, 0x4000
	s_mov_b32 m0, s35
	s_add_i32 s36, s35, 0x2000
	buffer_load_dwordx4 v138, s[4:7], s21 offen lds
	s_or_b32 s21, s16, 0x6000
	s_mov_b32 m0, s36
	s_add_i32 s37, s27, 0x8000
	buffer_load_dwordx4 v138, s[4:7], s21 offen lds
	s_or_b32 s21, s20, 0x4000
	s_mov_b32 m0, s37
	s_add_i32 s38, s27, 0xa000
	buffer_load_dwordx4 v138, s[0:3], s21 offen lds
	s_add_i32 s21, 16, 0x1c000
	s_or_b32 s20, s20, 0x6000
	s_mov_b32 m0, s38
	s_add_i32 s39, s21, s12
	buffer_load_dwordx4 v138, s[0:3], s20 offen lds
	s_add_i32 s20, s16, 0x168000
	s_mov_b32 m0, s39
	s_add_i32 s40, s39, 0x2000
	buffer_load_dwordx4 v138, s[4:7], s20 offen lds
	s_add_i32 s16, s16, 0x16a000
	s_mov_b32 m0, s40
	s_lshl_b32 s33, s13, 8
	buffer_load_dwordx4 v138, s[4:7], s16 offen lds
	s_lshr_b32 s6, s14, 8
	s_bfe_u32 s7, s14, 0x20006
	s_lshl_b32 s47, s15, 8
	s_cmp_eq_u32 s6, 1
	s_cselect_b64 s[12:13], -1, 0
	s_lshl_b32 s16, s7, 12
	s_waitcnt vmcnt(16)
	v_lshlrev_b32_e32 v2, 6, v174
	v_lshlrev_b32_e32 v3, 2, v174
	s_add_i32 s41, s27, 0xc000
	s_add_i32 s42, s27, 0xe000
	v_and_b32_e32 v0, 15, v174
	v_and_b32_e32 v1, 48, v174
	v_and_b32_e32 v2, 0x3c0, v2
	v_and_b32_e32 v3, 32, v3
	s_cmpk_lt_u32 s14, 0x100
	v_lshrrev_b32_e32 v8, 2, v174
	v_bitop3_b32 v2, v2, v3, v1 bitop3:0x36
	s_cselect_b64 s[14:15], -1, 0
	v_lshl_or_b32 v139, s6, 6, v0
	v_and_b32_e32 v8, 12, v8
	s_lshl_b32 s6, s6, 13
	v_lshl_or_b32 v0, v0, 6, v1
	s_waitcnt vmcnt(15)
	v_add_u32_e32 v4, s18, v2
	v_add_u32_e32 v5, s24, v2
	v_add_u32_e32 v6, s25, v2
	v_add_u32_e32 v7, s21, v2
	v_lshl_or_b32 v140, s7, 5, v8
	v_xad_u32 v0, v0, v3, 16
	v_add_u32_e32 v1, 16, v2
	s_or_b32 s7, s6, 0x800
	s_or_b32 s18, s6, 0x1000
	s_or_b32 s20, s6, 0x1800
	s_mov_b32 s43, 0
	v_add_u32_e32 v141, s16, v4
	v_add_u32_e32 v142, s6, v0
	v_add_u32_e32 v143, s7, v1
	v_add_u32_e32 v144, s18, v1
	v_add_u32_e32 v145, s20, v1
	v_add_u32_e32 v146, s16, v5
	v_add_u32_e32 v147, s16, v6
	v_add_u32_e32 v148, s16, v7
	s_mov_b32 s16, 0x3a000000
	s_mov_b32 s44, 0x800000
	v_mov_b32_e32 v129, 0
	s_mov_b32 s18, 0x3f9837f0
	s_waitcnt vmcnt(0)
	s_branch .LBB0_626

; #define WAIT_V(n) asm volatile("s_waitcnt vmcnt(" #n ")" ::: "memory")
; #define BAR __builtin_amdgcn_s_barrier()
; template <int EPI>
; __device__ __forceinline__ void gemm_phase(const u16* __restrict__ A, const u16* __restrict__ Bt, const int K,
;                                            const int nN, char* shm, const EpiArgs& ea) {
;     ...
;     WAIT_V(0);
;     if (wr == 1) BAR;
;     BAR;
;     BAR;
.LBB0_628:
	s_waitcnt vmcnt(40)
	s_andn2_b64 vcc, exec, s[12:13]
	s_cbranch_vccnz .LBB0_630
	s_barrier
